# hand-written fix_l2 (in-place K rope, 18 heads) with dword accesses instead of 2-byte accesses
# baseline (speedup 1.0000x reference)
.LBB0_709:
	v_readlane_b32 s0, v254, 20
	s_cmp_eq_u32 s0, 2
	s_cselect_b64 s[22:23], -1, 0
	s_cmp_lg_u32 s0, 2
	s_cselect_b64 s[12:13], -1, 0
	s_and_b64 vcc, exec, s[12:13]
	s_cbranch_vccnz .LBB0_770
	v_mov_b32_e32 v0, v198
	s_movk_i32 s0, 0x2000
	v_ashrrev_i32_e32 v2, 6, v0
	v_add_u32_e32 v2, s77, v2
	v_cmp_gt_i32_e32 vcc, s0, v2
	s_and_saveexec_b64 s[4:5], vcc
	s_cbranch_execz .LBB0_717
	v_readfirstlane_b32 s6, v198
	s_nop 1
	s_lshr_b32 s6, s6, 6
	s_add_i32 s6, s6, s77
	v_readlane_b32 s7, v253, 55
	s_nop 1
	s_lshr_b32 s7, s7, 1
	s_add_u32 s8, s84, 0x9d00000
	s_addc_u32 s9, s85, 0
	s_add_u32 s0, s84, 0x16f00000
	s_addc_u32 s1, s85, 0
	v_and_b32_e32 v3, 63, v198
	v_and_b32_e32 v56, 31, v3
	v_lshrrev_b32_e32 v57, 5, v3
	v_lshlrev_b32_e32 v58, 4, v56
	v_lshlrev_b32_e32 v56, 2, v56
	v_lshl_or_b32 v3, v57, 8, v56
	v_add_u32_e32 v3, 0x1a00, v3
	v_mov_b32_e32 v61, 0
	v_mov_b32_e32 v63, 0
.Lfixl2_loop:
	s_cmp_ge_u32 s6, 0x2000
	s_cbranch_scc1 .Lfixl2_done
	s_mul_i32 s100, s6, 0x4400
	v_add_u32_e32 v60, s100, v3
	v_lshl_add_u64 v[4:5], v[60:61], 0, s[8:9]
	s_lshl_b32 s100, s6, 9
	v_add_u32_e32 v62, s100, v58
	v_lshl_add_u64 v[6:7], v[62:63], 0, s[0:1]
	global_load_dwordx4 v[8:11], v[6:7], off
	global_load_dword v12, v[4:5], off offset:-2048
	global_load_dword v13, v[4:5], off offset:-1920
	global_load_dword v14, v[4:5], off offset:-1536
	global_load_dword v15, v[4:5], off offset:-1408
	global_load_dword v16, v[4:5], off offset:-1024
	global_load_dword v17, v[4:5], off offset:-896
	global_load_dword v18, v[4:5], off offset:-512
	global_load_dword v19, v[4:5], off offset:-384
	global_load_dword v20, v[4:5], off offset:0
	global_load_dword v21, v[4:5], off offset:128
	global_load_dword v22, v[4:5], off offset:512
	global_load_dword v23, v[4:5], off offset:640
	global_load_dword v24, v[4:5], off offset:1024
	global_load_dword v25, v[4:5], off offset:1152
	global_load_dword v26, v[4:5], off offset:1536
	global_load_dword v27, v[4:5], off offset:1664
	global_load_dword v28, v[4:5], off offset:2048
	global_load_dword v29, v[4:5], off offset:2176
	s_add_i32 s101, s6, s7
	s_cmp_lt_u32 s101, 0x2000
	s_cselect_b32 s101, s101, s6
	s_mul_i32 s100, s101, 0x4400
	v_add_u32_e32 v60, s100, v3
	v_lshl_add_u64 v[52:53], v[60:61], 0, s[8:9]
	s_lshl_b32 s100, s101, 9
	v_add_u32_e32 v62, s100, v58
	v_lshl_add_u64 v[54:55], v[62:63], 0, s[0:1]
	global_load_dwordx4 v[30:33], v[54:55], off
	global_load_dword v34, v[52:53], off offset:-2048
	global_load_dword v35, v[52:53], off offset:-1920
	global_load_dword v36, v[52:53], off offset:-1536
	global_load_dword v37, v[52:53], off offset:-1408
	global_load_dword v38, v[52:53], off offset:-1024
	global_load_dword v39, v[52:53], off offset:-896
	global_load_dword v40, v[52:53], off offset:-512
	global_load_dword v41, v[52:53], off offset:-384
	global_load_dword v42, v[52:53], off offset:0
	global_load_dword v43, v[52:53], off offset:128
	global_load_dword v44, v[52:53], off offset:512
	global_load_dword v45, v[52:53], off offset:640
	global_load_dword v46, v[52:53], off offset:1024
	global_load_dword v47, v[52:53], off offset:1152
	global_load_dword v48, v[52:53], off offset:1536
	global_load_dword v49, v[52:53], off offset:1664
	global_load_dword v50, v[52:53], off offset:2048
	global_load_dword v51, v[52:53], off offset:2176
	s_waitcnt vmcnt(19)
	v_lshlrev_b32_e32 v64, 16, v12
	v_and_b32_e32 v65, 0xffff0000, v12
	v_lshlrev_b32_e32 v66, 16, v13
	v_and_b32_e32 v67, 0xffff0000, v13
	v_mul_f32_e32 v68, v9, v66
	v_fma_f32 v68, v8, v64, -v68
	v_mul_f32_e32 v69, v8, v66
	v_fmac_f32_e32 v69, v9, v64
	v_mul_f32_e32 v70, v11, v67
	v_fma_f32 v70, v10, v65, -v70
	v_mul_f32_e32 v71, v10, v67
	v_fmac_f32_e32 v71, v11, v65
	v_cvt_pk_bf16_f32 v68, v68, v70
	v_cvt_pk_bf16_f32 v69, v69, v71
	global_store_dword v[4:5], v68, off offset:-2048
	global_store_dword v[4:5], v69, off offset:-1920
	v_lshlrev_b32_e32 v64, 16, v14
	v_and_b32_e32 v65, 0xffff0000, v14
	v_lshlrev_b32_e32 v66, 16, v15
	v_and_b32_e32 v67, 0xffff0000, v15
	v_mul_f32_e32 v68, v9, v66
	v_fma_f32 v68, v8, v64, -v68
	v_mul_f32_e32 v69, v8, v66
	v_fmac_f32_e32 v69, v9, v64
	v_mul_f32_e32 v70, v11, v67
	v_fma_f32 v70, v10, v65, -v70
	v_mul_f32_e32 v71, v10, v67
	v_fmac_f32_e32 v71, v11, v65
	v_cvt_pk_bf16_f32 v68, v68, v70
	v_cvt_pk_bf16_f32 v69, v69, v71
	global_store_dword v[4:5], v68, off offset:-1536
	global_store_dword v[4:5], v69, off offset:-1408
	v_lshlrev_b32_e32 v64, 16, v16
	v_and_b32_e32 v65, 0xffff0000, v16
	v_lshlrev_b32_e32 v66, 16, v17
	v_and_b32_e32 v67, 0xffff0000, v17
	v_mul_f32_e32 v68, v9, v66
	v_fma_f32 v68, v8, v64, -v68
	v_mul_f32_e32 v69, v8, v66
	v_fmac_f32_e32 v69, v9, v64
	v_mul_f32_e32 v70, v11, v67
	v_fma_f32 v70, v10, v65, -v70
	v_mul_f32_e32 v71, v10, v67
	v_fmac_f32_e32 v71, v11, v65
	v_cvt_pk_bf16_f32 v68, v68, v70
	v_cvt_pk_bf16_f32 v69, v69, v71
	global_store_dword v[4:5], v68, off offset:-1024
	global_store_dword v[4:5], v69, off offset:-896
	v_lshlrev_b32_e32 v64, 16, v18
	v_and_b32_e32 v65, 0xffff0000, v18
	v_lshlrev_b32_e32 v66, 16, v19
	v_and_b32_e32 v67, 0xffff0000, v19
	v_mul_f32_e32 v68, v9, v66
	v_fma_f32 v68, v8, v64, -v68
	v_mul_f32_e32 v69, v8, v66
	v_fmac_f32_e32 v69, v9, v64
	v_mul_f32_e32 v70, v11, v67
	v_fma_f32 v70, v10, v65, -v70
	v_mul_f32_e32 v71, v10, v67
	v_fmac_f32_e32 v71, v11, v65
	v_cvt_pk_bf16_f32 v68, v68, v70
	v_cvt_pk_bf16_f32 v69, v69, v71
	global_store_dword v[4:5], v68, off offset:-512
	global_store_dword v[4:5], v69, off offset:-384
	v_lshlrev_b32_e32 v64, 16, v20
	v_and_b32_e32 v65, 0xffff0000, v20
	v_lshlrev_b32_e32 v66, 16, v21
	v_and_b32_e32 v67, 0xffff0000, v21
	v_mul_f32_e32 v68, v9, v66
	v_fma_f32 v68, v8, v64, -v68
	v_mul_f32_e32 v69, v8, v66
	v_fmac_f32_e32 v69, v9, v64
	v_mul_f32_e32 v70, v11, v67
	v_fma_f32 v70, v10, v65, -v70
	v_mul_f32_e32 v71, v10, v67
	v_fmac_f32_e32 v71, v11, v65
	v_cvt_pk_bf16_f32 v68, v68, v70
	v_cvt_pk_bf16_f32 v69, v69, v71
	global_store_dword v[4:5], v68, off offset:0
	global_store_dword v[4:5], v69, off offset:128
	v_lshlrev_b32_e32 v64, 16, v22
	v_and_b32_e32 v65, 0xffff0000, v22
	v_lshlrev_b32_e32 v66, 16, v23
	v_and_b32_e32 v67, 0xffff0000, v23
	v_mul_f32_e32 v68, v9, v66
	v_fma_f32 v68, v8, v64, -v68
	v_mul_f32_e32 v69, v8, v66
	v_fmac_f32_e32 v69, v9, v64
	v_mul_f32_e32 v70, v11, v67
	v_fma_f32 v70, v10, v65, -v70
	v_mul_f32_e32 v71, v10, v67
	v_fmac_f32_e32 v71, v11, v65
	v_cvt_pk_bf16_f32 v68, v68, v70
	v_cvt_pk_bf16_f32 v69, v69, v71
	global_store_dword v[4:5], v68, off offset:512
	global_store_dword v[4:5], v69, off offset:640
	v_lshlrev_b32_e32 v64, 16, v24
	v_and_b32_e32 v65, 0xffff0000, v24
	v_lshlrev_b32_e32 v66, 16, v25
	v_and_b32_e32 v67, 0xffff0000, v25
	v_mul_f32_e32 v68, v9, v66
	v_fma_f32 v68, v8, v64, -v68
	v_mul_f32_e32 v69, v8, v66
	v_fmac_f32_e32 v69, v9, v64
	v_mul_f32_e32 v70, v11, v67
	v_fma_f32 v70, v10, v65, -v70
	v_mul_f32_e32 v71, v10, v67
	v_fmac_f32_e32 v71, v11, v65
	v_cvt_pk_bf16_f32 v68, v68, v70
	v_cvt_pk_bf16_f32 v69, v69, v71
	global_store_dword v[4:5], v68, off offset:1024
	global_store_dword v[4:5], v69, off offset:1152
	v_lshlrev_b32_e32 v64, 16, v26
	v_and_b32_e32 v65, 0xffff0000, v26
	v_lshlrev_b32_e32 v66, 16, v27
	v_and_b32_e32 v67, 0xffff0000, v27
	v_mul_f32_e32 v68, v9, v66
	v_fma_f32 v68, v8, v64, -v68
	v_mul_f32_e32 v69, v8, v66
	v_fmac_f32_e32 v69, v9, v64
	v_mul_f32_e32 v70, v11, v67
	v_fma_f32 v70, v10, v65, -v70
	v_mul_f32_e32 v71, v10, v67
	v_fmac_f32_e32 v71, v11, v65
	v_cvt_pk_bf16_f32 v68, v68, v70
	v_cvt_pk_bf16_f32 v69, v69, v71
	global_store_dword v[4:5], v68, off offset:1536
	global_store_dword v[4:5], v69, off offset:1664
	v_lshlrev_b32_e32 v64, 16, v28
	v_and_b32_e32 v65, 0xffff0000, v28
	v_lshlrev_b32_e32 v66, 16, v29
	v_and_b32_e32 v67, 0xffff0000, v29
	v_mul_f32_e32 v68, v9, v66
	v_fma_f32 v68, v8, v64, -v68
	v_mul_f32_e32 v69, v8, v66
	v_fmac_f32_e32 v69, v9, v64
	v_mul_f32_e32 v70, v11, v67
	v_fma_f32 v70, v10, v65, -v70
	v_mul_f32_e32 v71, v10, v67
	v_fmac_f32_e32 v71, v11, v65
	v_cvt_pk_bf16_f32 v68, v68, v70
	v_cvt_pk_bf16_f32 v69, v69, v71
	global_store_dword v[4:5], v68, off offset:2048
	global_store_dword v[4:5], v69, off offset:2176
	s_cmp_eq_u32 s101, s6
	s_cbranch_scc1 .Lfixl2_skipB
	s_waitcnt vmcnt(18)
	v_lshlrev_b32_e32 v64, 16, v34
	v_and_b32_e32 v65, 0xffff0000, v34
	v_lshlrev_b32_e32 v66, 16, v35
	v_and_b32_e32 v67, 0xffff0000, v35
	v_mul_f32_e32 v68, v31, v66
	v_fma_f32 v68, v30, v64, -v68
	v_mul_f32_e32 v69, v30, v66
	v_fmac_f32_e32 v69, v31, v64
	v_mul_f32_e32 v70, v33, v67
	v_fma_f32 v70, v32, v65, -v70
	v_mul_f32_e32 v71, v32, v67
	v_fmac_f32_e32 v71, v33, v65
	v_cvt_pk_bf16_f32 v68, v68, v70
	v_cvt_pk_bf16_f32 v69, v69, v71
	global_store_dword v[52:53], v68, off offset:-2048
	global_store_dword v[52:53], v69, off offset:-1920
	v_lshlrev_b32_e32 v64, 16, v36
	v_and_b32_e32 v65, 0xffff0000, v36
	v_lshlrev_b32_e32 v66, 16, v37
	v_and_b32_e32 v67, 0xffff0000, v37
	v_mul_f32_e32 v68, v31, v66
	v_fma_f32 v68, v30, v64, -v68
	v_mul_f32_e32 v69, v30, v66
	v_fmac_f32_e32 v69, v31, v64
	v_mul_f32_e32 v70, v33, v67
	v_fma_f32 v70, v32, v65, -v70
	v_mul_f32_e32 v71, v32, v67
	v_fmac_f32_e32 v71, v33, v65
	v_cvt_pk_bf16_f32 v68, v68, v70
	v_cvt_pk_bf16_f32 v69, v69, v71
	global_store_dword v[52:53], v68, off offset:-1536
	global_store_dword v[52:53], v69, off offset:-1408
	v_lshlrev_b32_e32 v64, 16, v38
	v_and_b32_e32 v65, 0xffff0000, v38
	v_lshlrev_b32_e32 v66, 16, v39
	v_and_b32_e32 v67, 0xffff0000, v39
	v_mul_f32_e32 v68, v31, v66
	v_fma_f32 v68, v30, v64, -v68
	v_mul_f32_e32 v69, v30, v66
	v_fmac_f32_e32 v69, v31, v64
	v_mul_f32_e32 v70, v33, v67
	v_fma_f32 v70, v32, v65, -v70
	v_mul_f32_e32 v71, v32, v67
	v_fmac_f32_e32 v71, v33, v65
	v_cvt_pk_bf16_f32 v68, v68, v70
	v_cvt_pk_bf16_f32 v69, v69, v71
	global_store_dword v[52:53], v68, off offset:-1024
	global_store_dword v[52:53], v69, off offset:-896
	v_lshlrev_b32_e32 v64, 16, v40
	v_and_b32_e32 v65, 0xffff0000, v40
	v_lshlrev_b32_e32 v66, 16, v41
	v_and_b32_e32 v67, 0xffff0000, v41
	v_mul_f32_e32 v68, v31, v66
	v_fma_f32 v68, v30, v64, -v68
	v_mul_f32_e32 v69, v30, v66
	v_fmac_f32_e32 v69, v31, v64
	v_mul_f32_e32 v70, v33, v67
	v_fma_f32 v70, v32, v65, -v70
	v_mul_f32_e32 v71, v32, v67
	v_fmac_f32_e32 v71, v33, v65
	v_cvt_pk_bf16_f32 v68, v68, v70
	v_cvt_pk_bf16_f32 v69, v69, v71
	global_store_dword v[52:53], v68, off offset:-512
	global_store_dword v[52:53], v69, off offset:-384
	v_lshlrev_b32_e32 v64, 16, v42
	v_and_b32_e32 v65, 0xffff0000, v42
	v_lshlrev_b32_e32 v66, 16, v43
	v_and_b32_e32 v67, 0xffff0000, v43
	v_mul_f32_e32 v68, v31, v66
	v_fma_f32 v68, v30, v64, -v68
	v_mul_f32_e32 v69, v30, v66
	v_fmac_f32_e32 v69, v31, v64
	v_mul_f32_e32 v70, v33, v67
	v_fma_f32 v70, v32, v65, -v70
	v_mul_f32_e32 v71, v32, v67
	v_fmac_f32_e32 v71, v33, v65
	v_cvt_pk_bf16_f32 v68, v68, v70
	v_cvt_pk_bf16_f32 v69, v69, v71
	global_store_dword v[52:53], v68, off offset:0
	global_store_dword v[52:53], v69, off offset:128
	v_lshlrev_b32_e32 v64, 16, v44
	v_and_b32_e32 v65, 0xffff0000, v44
	v_lshlrev_b32_e32 v66, 16, v45
	v_and_b32_e32 v67, 0xffff0000, v45
	v_mul_f32_e32 v68, v31, v66
	v_fma_f32 v68, v30, v64, -v68
	v_mul_f32_e32 v69, v30, v66
	v_fmac_f32_e32 v69, v31, v64
	v_mul_f32_e32 v70, v33, v67
	v_fma_f32 v70, v32, v65, -v70
	v_mul_f32_e32 v71, v32, v67
	v_fmac_f32_e32 v71, v33, v65
	v_cvt_pk_bf16_f32 v68, v68, v70
	v_cvt_pk_bf16_f32 v69, v69, v71
	global_store_dword v[52:53], v68, off offset:512
	global_store_dword v[52:53], v69, off offset:640
	v_lshlrev_b32_e32 v64, 16, v46
	v_and_b32_e32 v65, 0xffff0000, v46
	v_lshlrev_b32_e32 v66, 16, v47
	v_and_b32_e32 v67, 0xffff0000, v47
	v_mul_f32_e32 v68, v31, v66
	v_fma_f32 v68, v30, v64, -v68
	v_mul_f32_e32 v69, v30, v66
	v_fmac_f32_e32 v69, v31, v64
	v_mul_f32_e32 v70, v33, v67
	v_fma_f32 v70, v32, v65, -v70
	v_mul_f32_e32 v71, v32, v67
	v_fmac_f32_e32 v71, v33, v65
	v_cvt_pk_bf16_f32 v68, v68, v70
	v_cvt_pk_bf16_f32 v69, v69, v71
	global_store_dword v[52:53], v68, off offset:1024
	global_store_dword v[52:53], v69, off offset:1152
	v_lshlrev_b32_e32 v64, 16, v48
	v_and_b32_e32 v65, 0xffff0000, v48
	v_lshlrev_b32_e32 v66, 16, v49
	v_and_b32_e32 v67, 0xffff0000, v49
	v_mul_f32_e32 v68, v31, v66
	v_fma_f32 v68, v30, v64, -v68
	v_mul_f32_e32 v69, v30, v66
	v_fmac_f32_e32 v69, v31, v64
	v_mul_f32_e32 v70, v33, v67
	v_fma_f32 v70, v32, v65, -v70
	v_mul_f32_e32 v71, v32, v67
	v_fmac_f32_e32 v71, v33, v65
	v_cvt_pk_bf16_f32 v68, v68, v70
	v_cvt_pk_bf16_f32 v69, v69, v71
	global_store_dword v[52:53], v68, off offset:1536
	global_store_dword v[52:53], v69, off offset:1664
	v_lshlrev_b32_e32 v64, 16, v50
	v_and_b32_e32 v65, 0xffff0000, v50
	v_lshlrev_b32_e32 v66, 16, v51
	v_and_b32_e32 v67, 0xffff0000, v51
	v_mul_f32_e32 v68, v31, v66
	v_fma_f32 v68, v30, v64, -v68
	v_mul_f32_e32 v69, v30, v66
	v_fmac_f32_e32 v69, v31, v64
	v_mul_f32_e32 v70, v33, v67
	v_fma_f32 v70, v32, v65, -v70
	v_mul_f32_e32 v71, v32, v67
	v_fmac_f32_e32 v71, v33, v65
	v_cvt_pk_bf16_f32 v68, v68, v70
	v_cvt_pk_bf16_f32 v69, v69, v71
	global_store_dword v[52:53], v68, off offset:2048
	global_store_dword v[52:53], v69, off offset:2176
.Lfixl2_skipB:
	s_lshl_b32 s100, s7, 1
	s_add_i32 s6, s6, s100
	s_waitcnt vmcnt(0)
	s_branch .Lfixl2_loop
.Lfixl2_done:
.LBB0_717:
	s_or_b64 exec, exec, s[4:5]
	s_waitcnt vmcnt(0)
	s_waitcnt vmcnt(63) expcnt(7) lgkmcnt(15)
	s_barrier
	s_and_saveexec_b64 s[0:1], s[82:83]
	s_cbranch_execz .LBB0_769
	v_readlane_b32 s2, v253, 63
	s_waitcnt vmcnt(0) expcnt(0) lgkmcnt(0)
	s_nop 0
	v_mov_b32_e32 v0, s2
	ds_read_b32 v3, v0
	v_readlane_b32 s2, v254, 0
	s_waitcnt lgkmcnt(0)
	v_cmp_ne_u32_e32 vcc, 0, v3
	v_mov_b32_e32 v0, s2
	ds_read_b32 v2, v0
	s_cbranch_vccnz .LBB0_733
	s_mov_b32 s2, 1
	s_branch .LBB0_721
